# GEMM prologues: in-proj accumulator zeroing hoisted under the first stage-load wait; out-proj row-ratio ssq loads waited behind the stage loads
# speedup vs baseline: 1.0137x; 1.0039x over previous
.LBB0_132:
	s_or_b64 exec, exec, s[2:3]
	v_mov_b32_e32 v22, 0
	v_mov_b32_e32 v23, 0
	v_mov_b32_e32 v24, 0
	v_mov_b32_e32 v25, 0
	v_mov_b32_e32 v26, 0
	v_mov_b32_e32 v27, 0
	v_mov_b32_e32 v28, 0
	v_mov_b32_e32 v29, 0
	v_mov_b32_e32 v30, 0
	v_mov_b32_e32 v31, 0
	v_mov_b32_e32 v32, 0
	v_mov_b32_e32 v33, 0
	v_mov_b32_e32 v34, 0
	v_mov_b32_e32 v35, 0
	v_mov_b32_e32 v36, 0
	v_mov_b32_e32 v37, 0
	v_mov_b32_e32 v38, 0
	v_mov_b32_e32 v39, 0
	v_mov_b32_e32 v40, 0
	v_mov_b32_e32 v41, 0
	v_mov_b32_e32 v42, 0
	v_mov_b32_e32 v43, 0
	v_mov_b32_e32 v44, 0
	v_mov_b32_e32 v45, 0
	v_mov_b32_e32 v46, 0
	v_mov_b32_e32 v47, 0
	v_mov_b32_e32 v48, 0
	v_mov_b32_e32 v49, 0
	v_mov_b32_e32 v50, 0
	v_mov_b32_e32 v51, 0
	v_mov_b32_e32 v52, 0
	v_mov_b32_e32 v53, 0
	v_mov_b32_e32 v54, 0
	v_mov_b32_e32 v55, 0
	v_mov_b32_e32 v56, 0
	v_mov_b32_e32 v57, 0
	v_mov_b32_e32 v58, 0
	v_mov_b32_e32 v59, 0
	v_mov_b32_e32 v60, 0
	v_mov_b32_e32 v61, 0
	v_mov_b32_e32 v62, 0
	v_mov_b32_e32 v63, 0
	v_mov_b32_e32 v64, 0
	v_mov_b32_e32 v65, 0
	v_mov_b32_e32 v66, 0
	v_mov_b32_e32 v67, 0
	v_mov_b32_e32 v68, 0
	v_mov_b32_e32 v69, 0
	v_mov_b32_e32 v70, 0
	v_mov_b32_e32 v71, 0
	v_mov_b32_e32 v72, 0
	v_mov_b32_e32 v73, 0
	v_mov_b32_e32 v74, 0
	v_mov_b32_e32 v75, 0
	v_mov_b32_e32 v76, 0
	v_mov_b32_e32 v77, 0
	v_mov_b32_e32 v78, 0
	v_mov_b32_e32 v79, 0
	v_mov_b32_e32 v80, 0
	v_mov_b32_e32 v81, 0
	v_mov_b32_e32 v82, 0
	v_mov_b32_e32 v83, 0
	v_mov_b32_e32 v84, 0
	v_mov_b32_e32 v85, 0
	v_mov_b32_e32 v86, 0
	v_mov_b32_e32 v87, 0
	v_mov_b32_e32 v88, 0
	v_mov_b32_e32 v89, 0
	v_mov_b32_e32 v90, 0
	v_mov_b32_e32 v91, 0
	v_mov_b32_e32 v92, 0
	v_mov_b32_e32 v93, 0
	v_mov_b32_e32 v94, 0
	v_mov_b32_e32 v95, 0
	v_mov_b32_e32 v96, 0
	v_mov_b32_e32 v97, 0
	v_mov_b32_e32 v98, 0
	v_mov_b32_e32 v99, 0
	v_mov_b32_e32 v100, 0
	v_mov_b32_e32 v101, 0
	v_mov_b32_e32 v102, 0
	v_mov_b32_e32 v103, 0
	v_mov_b32_e32 v104, 0
	v_mov_b32_e32 v105, 0
	v_mov_b32_e32 v106, 0
	v_mov_b32_e32 v107, 0
	v_mov_b32_e32 v108, 0
	v_mov_b32_e32 v109, 0
	v_mov_b32_e32 v110, 0
	v_mov_b32_e32 v111, 0
	v_mov_b32_e32 v112, 0
	v_mov_b32_e32 v113, 0
	v_mov_b32_e32 v114, 0
	v_mov_b32_e32 v115, 0
	v_mov_b32_e32 v116, 0
	v_mov_b32_e32 v117, 0
	v_mov_b32_e32 v118, 0
	v_mov_b32_e32 v119, 0
	v_mov_b32_e32 v120, 0
	v_mov_b32_e32 v121, 0
	v_mov_b32_e32 v122, 0
	v_mov_b32_e32 v123, 0
	v_mov_b32_e32 v124, 0
	v_mov_b32_e32 v125, 0
	v_mov_b32_e32 v126, 0
	v_mov_b32_e32 v127, 0
	v_add_u32_e32 v157, s85, v17
	v_add_u32_e32 v158, 0x2000, v157
	v_readfirstlane_b32 s1, v157
	v_lshl_add_u64 v[10:11], v[10:11], 0, s[6:7]
	s_mov_b32 m0, s1
	v_readfirstlane_b32 s1, v158
	v_add_u32_e32 v159, 0x8000, v150
	s_waitcnt vmcnt(4)
	s_barrier
	global_load_lds_dwordx4 v[10:11], off
	v_lshl_add_u64 v[8:9], v[8:9], 0, s[6:7]
	s_mov_b32 m0, s1
	v_readfirstlane_b32 s1, v159
	v_add_u32_e32 v160, 0xa000, v150
	global_load_lds_dwordx4 v[8:9], off
	v_lshl_add_u64 v[6:7], v[6:7], 0, s[6:7]
	s_mov_b32 m0, s1
	v_readfirstlane_b32 s1, v160
	v_add_u32_e32 v161, s86, v17
	global_load_lds_dwordx4 v[6:7], off
	v_lshl_add_u64 v[4:5], v[4:5], 0, s[6:7]
	s_mov_b32 m0, s1
	v_readfirstlane_b32 s1, v161
	v_add_u32_e32 v162, 0x2000, v161
	global_load_lds_dwordx4 v[4:5], off
	v_lshl_add_u64 v[2:3], v[2:3], 0, s[6:7]
	s_mov_b32 m0, s1
	v_readfirstlane_b32 s1, v162
	global_load_lds_dwordx4 v[2:3], off
	v_lshl_add_u64 v[0:1], v[0:1], 0, s[6:7]
	s_mov_b32 m0, s1
	v_and_b32_e32 v20, 15, v140
	global_load_lds_dwordx4 v[0:1], off
	v_lshlrev_b32_e32 v1, 2, v140
	v_and_b32_e32 v21, 48, v140
	v_lshlrev_b32_e32 v0, 6, v20
	v_and_b32_e32 v1, 32, v1
	v_bitop3_b32 v0, v0, v1, v21 bitop3:0x36
	v_lshlrev_b32_e32 v2, 6, v140
	s_movk_i32 s1, 0x3c0
	v_add_u32_e32 v4, s33, v0
	v_add_u32_e32 v5, s84, v0
	v_add_u32_e32 v6, s85, v0
	v_add_u32_e32 v7, s86, v0
	v_add_u32_e32 v10, 16, v0
	v_and_or_b32 v0, v2, s1, v21
	v_and_b32_e32 v8, 0x3000, v2
	v_xad_u32 v11, v0, v1, 16
	v_lshlrev_b32_e32 v0, 15, v12
	v_lshlrev_b32_e32 v2, 15, v14
	v_and_b32_e32 v0, 0xffff0000, v0
	v_and_b32_e32 v2, 0xffff0000, v2
	v_lshl_add_u32 v0, v13, 12, v0
	v_and_b32_e32 v1, 1, v12
	s_add_u32 s2, s54, s30
	v_lshl_add_u32 v2, v16, 12, v2
	v_and_b32_e32 v3, 1, v14
	v_readlane_b32 s1, v255, 7
	v_lshl_or_b32 v0, v1, 6, v0
	s_addc_u32 s3, s55, s31
	v_lshl_or_b32 v2, v3, 6, v2
	s_add_i32 s1, s1, s4
	v_lshl_add_u32 v0, v15, 1, v0
	v_mov_b32_e32 v1, v133
	v_lshl_add_u32 v2, v18, 1, v2
	v_mov_b32_e32 v3, v133
	s_lshl_b32 s1, s1, 20
	v_lshl_add_u64 v[130:131], s[2:3], 0, v[0:1]
	v_lshl_add_u64 v[134:135], s[2:3], 0, v[2:3]
	s_add_u32 s2, s52, s1
	s_waitcnt vmcnt(6)
	v_lshlrev_b32_e32 v9, 13, v19
	s_addc_u32 s3, s53, 0
	v_or_b32_e32 v17, 0x800, v9
	v_or_b32_e32 v19, 0x1000, v9
	v_or_b32_e32 v20, 0x1800, v9
	v_lshl_add_u64 v[136:137], s[2:3], 0, v[0:1]
	v_mov_b32_e32 v0, 0
	v_lshl_add_u64 v[138:139], s[2:3], 0, v[2:3]
	s_mov_b32 s1, -2
	s_mov_b64 s[30:31], 0
	v_add_u32_e32 v164, v4, v8
	v_add_u32_e32 v146, v10, v9
	v_add_u32_e32 v145, v11, v17
	v_add_u32_e32 v144, v11, v19
	v_add_u32_e32 v143, v11, v20
	v_add_u32_e32 v163, v5, v8
	v_add_u32_e32 v154, v6, v8
	v_add_u32_e32 v149, v7, v8
	v_mov_b32_e32 v1, v0
	v_mov_b32_e32 v2, v0
	v_mov_b32_e32 v3, v0
	v_mov_b32_e32 v4, v0
	v_mov_b32_e32 v5, v0
	v_mov_b32_e32 v6, v0
	v_mov_b32_e32 v7, v0
	v_mov_b32_e32 v8, v0
	v_mov_b32_e32 v9, v0
	v_mov_b32_e32 v10, v0
	v_mov_b32_e32 v11, v0
	v_mov_b32_e32 v12, v0
	v_mov_b32_e32 v13, v0
	v_mov_b32_e32 v14, v0
	v_mov_b32_e32 v15, v0
	v_mov_b32_e32 v16, v0
	v_mov_b32_e32 v17, v0
	v_mov_b32_e32 v18, v0
	v_mov_b32_e32 v19, v0
	v_mov_b32_e32 v20, v0
	v_mov_b32_e32 v21, v0
	s_barrier

.LBB0_708:
	s_or_b32 s30, s35, s5
	s_lshl_b32 s6, s30, 8
	s_and_saveexec_b64 s[28:29], s[0:1]
	s_cbranch_execz .LBB0_710
	v_or_b32_e32 v176, s6, v204
	v_lshl_add_u64 v[0:1], v[176:177], 2, s[78:79]
	v_add_co_u32_e32 v2, vcc, 0x10000, v0
	s_nop 1
	v_addc_co_u32_e32 v3, vcc, 0, v1, vcc
	global_load_dword v252, v[2:3], off
	s_nop 0
	global_load_dword v253, v[0:1], off

.LBB0_712:
	s_or_b64 exec, exec, s[28:29]
	v_add_u32_e32 v153, s85, v8
	s_xor_b64 s[28:29], s[2:3], -1
	v_lshl_add_u64 v[12:13], s[8:9], 0, v[176:177]
	v_readfirstlane_b32 s2, v153
	v_add_u32_e32 v154, 0x2000, v153
	v_lshl_add_u64 v[14:15], s[8:9], 0, v[128:129]
	v_lshl_add_u64 v[12:13], v[12:13], 0, s[16:17]
	s_mov_b32 m0, s2
	v_readfirstlane_b32 s2, v154
	v_add_u32_e32 v155, 0x8000, v146
	s_waitcnt vmcnt(4)
	s_and_saveexec_b64 s[98:99], s[0:1]
	s_cbranch_execz .Lop_ratio_skip
	v_fmamk_f32 v251, v252, 0x3a800000, v209
	v_rsq_f32_e32 v251, v251
	v_fmamk_f32 v250, v253, 0x3a800000, v209
	v_rsq_f32_e32 v250, v250
	v_rcp_f32_e32 v251, v251
	s_nop 0
	v_mul_f32_e32 v250, v250, v251
	v_lshl_add_u32 v251, v204, 2, s39
	ds_write_b32 v251, v250
.Lop_ratio_skip:
	s_or_b64 exec, exec, s[98:99]
	s_barrier
	global_load_lds_dwordx4 v[12:13], off
	v_lshl_add_u64 v[12:13], v[14:15], 0, s[16:17]
	s_mov_b32 m0, s2
	v_readfirstlane_b32 s2, v155
	v_add_u32_e32 v156, 0xa000, v146
	global_load_lds_dwordx4 v[12:13], off
	v_lshl_add_u64 v[2:3], v[2:3], 0, s[16:17]
	s_mov_b32 m0, s2
	v_readfirstlane_b32 s2, v156
	v_add_u32_e32 v157, s86, v8
	v_lshl_add_u64 v[16:17], s[10:11], 0, v[176:177]
	global_load_lds_dwordx4 v[2:3], off
	v_lshl_add_u64 v[0:1], v[0:1], 0, s[16:17]
	s_mov_b32 m0, s2
	v_readfirstlane_b32 s2, v157
	v_add_u32_e32 v158, 0x2000, v157
	v_lshl_add_u64 v[18:19], s[10:11], 0, v[128:129]
	global_load_lds_dwordx4 v[0:1], off
	v_lshl_add_u64 v[0:1], v[16:17], 0, s[16:17]
	s_mov_b32 m0, s2
	v_readfirstlane_b32 s2, v158
	global_load_lds_dwordx4 v[0:1], off
	v_lshl_add_u64 v[0:1], v[18:19], 0, s[16:17]
	s_mov_b32 m0, s2
	v_and_b32_e32 v20, 15, v138
	global_load_lds_dwordx4 v[0:1], off
	v_lshlrev_b32_e32 v0, 2, v20
	v_and_b32_e32 v21, 48, v138
	v_add_u32_e32 v8, s39, v0
	v_lshlrev_b32_e32 v1, 6, v20
	v_and_b32_e32 v0, 32, v0
	v_bitop3_b32 v1, v1, v0, v21 bitop3:0x36
	v_lshlrev_b32_e32 v2, 6, v138
	v_add_u32_e32 v12, s33, v1
	v_add_u32_e32 v14, s84, v1
	v_add_u32_e32 v15, s85, v1
	v_add_u32_e32 v16, s86, v1
	v_and_b32_e32 v17, 0x3000, v2
	v_add_u32_e32 v18, 16, v1
	v_and_or_b32 v1, v2, s45, v21
	v_lshlrev_b32_e32 v2, 15, v7
	v_xad_u32 v19, v1, v0, 16
	v_lshlrev_b32_e32 v0, 15, v4
	v_and_b32_e32 v2, 0xffff0000, v2
	s_add_i32 s2, s5, s35
	s_mov_b32 s3, s7
	v_and_b32_e32 v0, 0xffff0000, v0
	v_lshl_add_u32 v2, v9, 12, v2
	v_and_b32_e32 v3, 1, v7
	s_lshl_b64 s[2:3], s[2:3], 20
	v_lshl_add_u32 v0, v5, 12, v0
	v_and_b32_e32 v1, 1, v4
	v_lshl_or_b32 v2, v3, 6, v2
	s_add_u32 s2, s72, s2
	v_lshlrev_b32_e32 v11, 13, v11
	v_lshl_or_b32 v0, v1, 6, v0
	v_lshl_add_u32 v2, v10, 1, v2
	v_mov_b32_e32 v3, v177
	s_addc_u32 s3, s73, s3
	s_waitcnt vmcnt(6)
	v_and_b32_e32 v13, 0xffffff00, v138
	v_or_b32_e32 v20, 0x800, v11
	v_or_b32_e32 v21, 0x1000, v11
	v_or_b32_e32 v22, 0x1800, v11
	v_lshl_add_u32 v0, v6, 1, v0
	v_mov_b32_e32 v1, v177
	v_lshl_add_u64 v[132:133], s[8:9], 0, v[2:3]
	v_lshl_add_u64 v[136:137], s[2:3], 0, v[2:3]
	v_mov_b32_e32 v2, v177
	v_lshl_add_u64 v[130:131], s[8:9], 0, v[0:1]
	v_lshl_add_u64 v[134:135], s[2:3], 0, v[0:1]
	v_mov_b32_e32 v0, v177
	v_add_u32_e32 v161, v8, v13
	v_add_u32_e32 v160, v12, v17
	v_add_u32_e32 v142, v18, v11
	v_add_u32_e32 v141, v19, v20
	v_add_u32_e32 v140, v19, v21
	v_add_u32_e32 v139, v19, v22
	v_add_u32_e32 v159, v14, v17
	v_add_u32_e32 v151, v15, v17
	v_add_u32_e32 v145, v16, v17
	v_mov_b64_e32 v[6:7], v[2:3]
	v_mov_b64_e32 v[14:15], v[2:3]
	v_mov_b64_e32 v[30:31], v[2:3]
	v_mov_b64_e32 v[66:67], v[2:3]
	v_mov_b64_e32 v[70:71], v[2:3]
	v_mov_b64_e32 v[74:75], v[2:3]
	v_mov_b64_e32 v[78:79], v[2:3]
	v_mov_b64_e32 v[82:83], v[2:3]
	v_mov_b64_e32 v[86:87], v[2:3]
	v_mov_b64_e32 v[90:91], v[2:3]
	v_mov_b64_e32 v[94:95], v[2:3]
	v_mov_b64_e32 v[98:99], v[2:3]
	v_mov_b64_e32 v[102:103], v[2:3]
	v_mov_b64_e32 v[106:107], v[2:3]
	v_mov_b64_e32 v[110:111], v[2:3]
	v_mov_b64_e32 v[114:115], v[2:3]
	v_mov_b64_e32 v[118:119], v[2:3]
	v_mov_b64_e32 v[122:123], v[2:3]
	v_mov_b64_e32 v[126:127], v[2:3]
	v_mov_b64_e32 v[62:63], v[2:3]
	v_mov_b64_e32 v[58:59], v[2:3]
	v_mov_b64_e32 v[54:55], v[2:3]
	v_mov_b64_e32 v[50:51], v[2:3]
	v_mov_b64_e32 v[46:47], v[2:3]
	v_mov_b64_e32 v[42:43], v[2:3]
	v_mov_b64_e32 v[38:39], v[2:3]
	v_mov_b64_e32 v[34:35], v[2:3]
	v_mov_b64_e32 v[26:27], v[2:3]
	v_mov_b64_e32 v[22:23], v[2:3]
	v_mov_b64_e32 v[18:19], v[2:3]
	v_mov_b64_e32 v[10:11], v[2:3]
	s_mov_b32 s35, -2
	s_mov_b64 s[2:3], 0
	v_mov_b64_e32 v[4:5], v[0:1]
	v_mov_b64_e32 v[12:13], v[0:1]
	v_mov_b64_e32 v[28:29], v[0:1]
	v_mov_b64_e32 v[64:65], v[0:1]
	v_mov_b64_e32 v[68:69], v[0:1]
	v_mov_b64_e32 v[72:73], v[0:1]
	v_mov_b64_e32 v[76:77], v[0:1]
	v_mov_b64_e32 v[80:81], v[0:1]
	v_mov_b64_e32 v[84:85], v[0:1]
	v_mov_b64_e32 v[88:89], v[0:1]
	v_mov_b64_e32 v[92:93], v[0:1]
	v_mov_b64_e32 v[96:97], v[0:1]
	v_mov_b64_e32 v[100:101], v[0:1]
	v_mov_b64_e32 v[104:105], v[0:1]
	v_mov_b64_e32 v[108:109], v[0:1]
	v_mov_b64_e32 v[112:113], v[0:1]
	v_mov_b64_e32 v[116:117], v[0:1]
	v_mov_b64_e32 v[120:121], v[0:1]
	v_mov_b64_e32 v[124:125], v[0:1]
	v_mov_b64_e32 v[60:61], v[0:1]
	v_mov_b64_e32 v[56:57], v[0:1]
	v_mov_b64_e32 v[52:53], v[0:1]
	v_mov_b64_e32 v[48:49], v[0:1]
	v_mov_b64_e32 v[44:45], v[0:1]
	v_mov_b64_e32 v[40:41], v[0:1]
	v_mov_b64_e32 v[36:37], v[0:1]
	v_mov_b64_e32 v[32:33], v[0:1]
	v_mov_b64_e32 v[24:25], v[0:1]
	v_mov_b64_e32 v[20:21], v[0:1]
	v_mov_b64_e32 v[16:17], v[0:1]
	v_mov_b64_e32 v[8:9], v[0:1]
	s_barrier
	s_branch .LBB0_714

	.amdhsa_kernel _Z9hymba_fwd6Params
		.amdhsa_group_segment_fixed_size 16
		.amdhsa_private_segment_fixed_size 0
		.amdhsa_kernarg_size 520
		.amdhsa_user_sgpr_count 2
		.amdhsa_user_sgpr_dispatch_ptr 0
		.amdhsa_user_sgpr_queue_ptr 0
		.amdhsa_user_sgpr_kernarg_segment_ptr 1
		.amdhsa_user_sgpr_dispatch_id 0
		.amdhsa_user_sgpr_kernarg_preload_length 0
		.amdhsa_user_sgpr_kernarg_preload_offset 0
		.amdhsa_user_sgpr_private_segment_size 0
		.amdhsa_uses_dynamic_stack 0
		.amdhsa_enable_private_segment 0
		.amdhsa_system_sgpr_workgroup_id_x 1
		.amdhsa_system_sgpr_workgroup_id_y 0
		.amdhsa_system_sgpr_workgroup_id_z 0
		.amdhsa_system_sgpr_workgroup_info 0
		.amdhsa_system_vgpr_workitem_id 2
		.amdhsa_next_free_vgpr 256
		.amdhsa_next_free_sgpr 102
		.amdhsa_accum_offset 256
		.amdhsa_reserve_vcc 1
		.amdhsa_float_round_mode_32 0
		.amdhsa_float_round_mode_16_64 0
		.amdhsa_float_denorm_mode_32 3
		.amdhsa_float_denorm_mode_16_64 3
		.amdhsa_dx10_clamp 1
		.amdhsa_ieee_mode 1
		.amdhsa_fp16_overflow 0
		.amdhsa_tg_split 0
		.amdhsa_exception_fp_ieee_invalid_op 0
		.amdhsa_exception_fp_denorm_src 0
		.amdhsa_exception_fp_ieee_div_zero 0
		.amdhsa_exception_fp_ieee_overflow 0
		.amdhsa_exception_fp_ieee_underflow 0
		.amdhsa_exception_fp_ieee_inexact 0
		.amdhsa_exception_int_div_zero 0
	.end_amdhsa_kernel

amdhsa.kernels:
  - .agpr_count:     0
    .args:
      - .offset:         0
        .size:           264
        .value_kind:     by_value
      - .offset:         264
        .size:           4
        .value_kind:     hidden_block_count_x
      - .offset:         268
        .size:           4
        .value_kind:     hidden_block_count_y
      - .offset:         272
        .size:           4
        .value_kind:     hidden_block_count_z
      - .offset:         276
        .size:           2
        .value_kind:     hidden_group_size_x
      - .offset:         278
        .size:           2
        .value_kind:     hidden_group_size_y
      - .offset:         280
        .size:           2
        .value_kind:     hidden_group_size_z
      - .offset:         282
        .size:           2
        .value_kind:     hidden_remainder_x
      - .offset:         284
        .size:           2
        .value_kind:     hidden_remainder_y
      - .offset:         286
        .size:           2
        .value_kind:     hidden_remainder_z
      - .offset:         304
        .size:           8
        .value_kind:     hidden_global_offset_x
      - .offset:         312
        .size:           8
        .value_kind:     hidden_global_offset_y
      - .offset:         320
        .size:           8
        .value_kind:     hidden_global_offset_z
      - .offset:         328
        .size:           2
        .value_kind:     hidden_grid_dims
      - .offset:         352
        .size:           8
        .value_kind:     hidden_multigrid_sync_arg
      - .offset:         384
        .size:           4
        .value_kind:     hidden_dynamic_lds_size
    .group_segment_fixed_size: 16
    .kernarg_segment_align: 8
    .kernarg_segment_size: 520
    .language:       OpenCL C
    .language_version:
      - 2
      - 0
    .max_flat_workgroup_size: 512
    .name:           _Z9hymba_fwd6Params
    .private_segment_fixed_size: 0
    .sgpr_count:     108
    .sgpr_spill_count: 22
    .symbol:         _Z9hymba_fwd6Params.kd
    .uniform_work_group_size: 1
    .uses_dynamic_stack: false
    .vgpr_count:     256
    .vgpr_spill_count: 0
    .wavefront_size: 64
